# attention unit start: barrier no longer waits for the previous unit's O stores to drain (vmcnt(0) -> lgkmcnt(0) before the unit-start barrier, MLA and diff)
# baseline (speedup 1.0000x reference)
; __global__ void __launch_bounds__(512, 2) mk_fwd(Args args) {
;     ...
;             for (int uidx = blockIdx.x; uidx < NBIG_M + (l == DEPTH - 1 ? 0 : 64 + NSM_M); uidx += G) {
;                 __syncthreads();
;                 int bh, qb; bool small;
;                 if (uidx < NBIG_M) { const int c = uidx & 255, i = uidx >> 8; bh = (c & 7) * 2 + ((c >> 3) >> 4) + 16 * i; qb = (c >> 3) & 15; small = false; }
;                 else { bh = uidx - NBIG_M - 64; qb = 0; small = true; if (bh < 0) continue; }
;                 const int b = bh >> 3, h = bh & 7; const size_t tk0 = (size_t)b * TPB, tq0 = tk0 + (small ? 0 : CTXL + qb * 256);
.LBB0_669:
	s_cmpk_gt_i32 s25, 0x1ff
	s_waitcnt lgkmcnt(0)
	s_barrier
	s_cbranch_scc1 .LBB0_671
	s_lshl_b32 s4, s25, 1
	s_and_b32 s4, s4, 14
	s_bfe_u32 s5, s25, 0x10007
	s_or_b32 s4, s4, s5
	s_ashr_i32 s5, s25, 4
	s_and_b32 s5, s5, -16
	s_or_b32 s26, s4, s5
	s_lshl_b32 s4, s25, 5
	s_and_b32 s4, s4, 0xf00
	s_add_i32 s30, s4, 0x100
	s_mov_b64 s[6:7], -1
	s_mov_b64 s[4:5], s[30:31]
	s_movk_i32 s30, 0x42
	s_cbranch_execz .LBB0_672
	s_branch .LBB0_673

; __global__ void __launch_bounds__(512, 2) mk_fwd(Args args) {
;     ...
;             for (int uidx = blockIdx.x; uidx < 512 + (l == DEPTH - 1 ? 0 : 32); uidx += G) {
;                 __syncthreads();
;                 int combo, qb; bool small;
;                 if (uidx < 512) { const int c = uidx & 255, i = uidx >> 8; combo = (c & 7) * 2 + ((c >> 3) >> 4) + 16 * i; qb = (c >> 3) & 15; small = false; }
;                 else { combo = uidx - 512; qb = 0; small = true; }
;                 const int mp = combo & 1, h = (combo >> 1) & 3, b = combo >> 3;
;                 const size_t tk0 = (size_t)b * TPB, tq0 = tk0 + (small ? 0 : CTXL + qb * 256);
.LBB0_694:
	s_cmpk_gt_i32 s25, 0x1ff
	s_mov_b64 s[6:7], -1
	s_waitcnt lgkmcnt(0)
	s_barrier
	s_cbranch_scc1 .LBB0_696
	s_lshl_b32 s4, s25, 1
	s_and_b32 s4, s4, 14
	s_bfe_u32 s5, s25, 0x10007
	s_or_b32 s4, s4, s5
	s_ashr_i32 s5, s25, 4
	s_and_b32 s5, s5, -16
	s_or_b32 s10, s4, s5
	s_lshl_b32 s4, s25, 5
	s_and_b32 s4, s4, 0xf00
	s_add_i32 s30, s4, 0x100
	s_mov_b64 s[6:7], 0
	s_mov_b64 s[4:5], s[30:31]
